# phase2 LoRA balance: 48 g-gate tiles of prompt rows deferred to phase 5 filler blocks, every block runs exactly 3 LoRA tiles in phase 2
# baseline (speedup 1.0000x reference)
.LBB0_271:
	s_mov_b32 s101, 0
	s_cmpk_gt_i32 s2, 0x62f
	s_cbranch_scc1 .LBB0_435
.Llora_pre:
	v_lshrrev_b32_e32 v1, 2, v218
	v_lshrrev_b32_e32 v0, 1, v218
	v_and_b32_e32 v1, 12, v1
	s_movk_i32 s0, 0x1c0
	v_and_or_b32 v0, v0, s0, v1
	v_and_b32_e32 v1, 0x4f, v218
	v_and_b32_e32 v2, 16, v218
	v_lshlrev_b32_e32 v192, 9, v0
	v_bitop3_b32 v0, v1, v218, 16 bitop3:0x72
	s_add_u32 s20, s84, 0x1080000
	v_and_b32_e32 v3, 0x5f, v218
	v_lshlrev_b32_e32 v194, 2, v0
	v_bitop3_b32 v0, v1, v2, 48 bitop3:0x36
	s_addc_u32 s21, s85, 0
	v_lshl_or_b32 v193, v3, 2, v192
	v_lshlrev_b32_e32 v195, 2, v0
	v_mov_b32_e32 v149, 0
	s_movk_i32 s3, 0x1200
	s_movk_i32 s26, 0x4000
	s_movk_i32 s27, 0x3fff
	s_movk_i32 s28, 0x700
	s_mov_b32 s29, 0x7ffffc0
	s_movk_i32 s30, 0xa0
	s_movk_i32 s31, 0x1c00
	v_mov_b32_e32 v196, 0x7ff
	v_mov_b32_e32 v197, 0x1b00
	s_mov_b32 s34, s2
	s_cmp_eq_u32 s101, 1
	s_cbranch_scc0 .LBB0_274
	s_add_i32 s34, s2, 0x400
	s_branch .LBB0_274
.LBB0_273:
	s_cmp_eq_u32 s101, 1
	s_cbranch_scc1 .Llora_ret
	s_add_i32 s34, s34, s94
	s_cmpk_lt_i32 s34, 0x600
	s_cbranch_scc0 .LBB0_435
	s_cmpk_lt_i32 s34, 0x5d0
	s_cbranch_scc1 .LBB0_274
	s_add_i32 s34, s34, 48

.Llora_call:
	s_cmpk_lt_u32 s2, 0x1d0
	s_cbranch_scc1 .LBB0_795
	s_waitcnt vmcnt(0) lgkmcnt(0)
	s_barrier
	v_readlane_b32 s80, v242, 17
	v_readlane_b32 s81, v242, 18
	v_readlane_b32 s82, v242, 19
	v_readlane_b32 s83, v242, 20
	v_readlane_b32 s84, v242, 21
	v_readlane_b32 s85, v242, 22
	v_readlane_b32 s86, v242, 23
	v_readlane_b32 s87, v242, 24
	v_readlane_b32 s88, v242, 25
	v_readlane_b32 s89, v242, 26
	v_readlane_b32 s90, v242, 27
	v_readlane_b32 s91, v242, 28
	v_readlane_b32 s92, v242, 29
	v_readlane_b32 s93, v242, 30
	v_readlane_b32 s94, v242, 31
	v_readlane_b32 s95, v242, 32
	s_mov_b32 s101, 1
	s_branch .Llora_pre
.Llora_ret:
	s_mov_b32 s101, 0
	v_readlane_b32 s92, v242, 29
	v_readlane_b32 s93, v242, 30
	v_readlane_b32 s94, v242, 31
	v_readlane_b32 s95, v242, 32
	s_nop 1
	s_branch .LBB0_795
